# diff loop K-fragment LDS reads bank-conflict-free (ds_read_b128 -> 2x ds_read_b64 with halves exchanged on odd quads, Q fragments exchanged to match), on top of v34
# baseline (speedup 1.0000x reference)
; __device__ __forceinline__ float uniform_f(float x) { return __uint_as_float((unsigned)__builtin_amdgcn_readfirstlane((int)__float_as_uint(x))); }
; #define DF_COMMIT(buf) do { LAS unsigned char* bb_ = lds + (buf) * DF_BUF; \
;         _Pragma("unroll") for (int i_ = 0; i_ < 2; ++i_) { const int id_ = tid + 512 * i_, kr_ = id_ >> 5, kc_ = id_ & 31, vr_ = id_ >> 2, vc_ = id_ & 3; \
;             *(LAS u32x4*)(bb_ + kr_ * DF_KP + kc_ * 16) = kreg[i_]; *(LAS u32x4*)(bb_ + DF_KBYTES + vr_ * VP + vc_ * 16) = vreg[i_]; } } while (0)
; __device__ __forceinline__ void wg_diff_task(ParamsCP pp, int layer, LAS unsigned char* lds, int b, int h, int qb, int tid_in) {
;     ...
;     const bf16_t* PROJ = (const bf16_t*)(pp->ws + WS_BIG + BIG_PROJ); const bf16_t* VT = (const bf16_t*)(pp->ws + WS_BIG + BIG_VT);
;     const int lane = tid & 63, wave = __builtin_amdgcn_readfirstlane(tid >> 6), c16 = lane & 15, quad = lane >> 4;
;     const size_t qcol = PBUF + h * 256, kcol = PBUF + 1024 + h * 256;
;     const int vrow0 = V_DIFF + h * 256;
;     const int jraw = qb * 8 + wave; const bool active = jraw < 129; const int jq = active ? jraw : 128;
;     const int qrow0 = tile_row(b, jq);
;     const float* misc = (const float*)(pp->ws + WS_MISC) + 16 * layer;
;     const float lam = uniform_f(misc[0]), cb = uniform_f(misc[1] * LOG2E), sc = 0.08838834764831845f * LOG2E;
;     bf16x8 qf0[4], qf1[4];
;     { const bf16_t* qp = PROJ + (size_t)(qrow0 + c16) * PP + qcol + 8 * quad;
; #pragma unroll
;         for (int ks = 0; ks < 4; ++ks) { qf0[ks] = *(const bf16x8*)(qp + 32 * ks); qf1[ks] = *(const bf16x8*)(qp + 128 + 32 * ks); } }
;     f32x4 acc0[16], acc1[16];
; #pragma unroll
;     for (int e0 = 0; e0 < 16; ++e0) { acc0[e0] = (f32x4){0.f, 0.f, 0.f, 0.f}; acc1[e0] = (f32x4){0.f, 0.f, 0.f, 0.f}; }
;     float ls0 = 0.f, ls1 = 0.f;
;     u32x4 kreg[2], vreg[2];
;     ...
;     __syncthreads();
;     DF_ISSUE(0); DF_COMMIT(0);
;     __syncthreads();
.Lmx_d_noat:
	s_mov_b64 exec, s[4:5]
	v_and_b32_e32 v207, 15, v2
	v_add_u32_e32 v4, s30, v207
	s_lshl_b32 s24, s10, 8
	v_ashrrev_i32_e32 v5, 31, v4
	s_ashr_i32 s25, s24, 31
	v_lshlrev_b64 v[4:5], 12, v[4:5]
	v_bfe_u32 v208, v2, 4, 2
	v_lshl_add_u64 v[4:5], s[84:85], 0, v[4:5]
	s_lshl_b64 s[4:5], s[24:25], 1
	v_lshl_add_u64 v[4:5], v[4:5], 0, s[4:5]
	v_lshlrev_b32_e32 v0, 4, v208
	v_lshl_add_u64 v[4:5], v[4:5], 0, v[0:1]
	v_and_b32_e32 v253, 1, v208
	v_lshl_or_b32 v0, v253, 3, v0
	s_mov_b64 s[10:11], 0x8100000
	s_add_i32 s38, s24, 0x400
	v_lshl_add_u64 v[6:7], v[4:5], 0, s[10:11]
	s_mov_b32 s10, 0x8100000
	s_bitset1_b32 s9, 8
	v_add_co_u32_e32 v4, vcc, s10, v4
	s_add_u32 s4, s84, s4
	v_lshlrev_b32_e32 v10, 4, v2
	v_addc_co_u32_e32 v5, vcc, 0, v5, vcc
	s_addc_u32 s5, s85, s5
	v_and_b32_e32 v180, 0x1f0, v10
	v_mov_b32_e32 v181, v1
	global_load_dwordx4 v[114:117], v[4:5], off
	global_load_dwordx2 v[178:179], v1, s[20:21]
	global_load_dwordx4 v[118:121], v[6:7], off offset:64
	global_load_dwordx4 v[122:125], v[6:7], off offset:256
	global_load_dwordx4 v[126:129], v[6:7], off offset:320
	global_load_dwordx4 v[134:137], v[6:7], off offset:128
	global_load_dwordx4 v[138:141], v[6:7], off offset:192
	global_load_dwordx4 v[142:145], v[6:7], off offset:384
	global_load_dwordx4 v[146:149], v[6:7], off offset:448
	v_and_b32_e32 v3, 2, v2
	v_lshl_add_u64 v[4:5], s[4:5], 0, v[180:181]
	s_mov_b64 s[4:5], 0x8100800
	v_lshlrev_b32_e32 v6, 3, v2
	v_lshl_add_u64 v[182:183], v[4:5], 0, s[4:5]
	v_mov_b32_e32 v4, s9
	v_mov_b32_e32 v11, s8
	v_cmp_eq_u32_e64 s[8:9], 0, v3
	v_and_b32_e32 v181, 8, v6
	v_ashrrev_i32_e32 v209, 5, v2
	v_cndmask_b32_e64 v3, v4, v11, s[8:9]
	v_or_b32_e32 v4, v3, v181
	v_mov_b32_e32 v3, s37
	v_cmp_gt_i32_e64 s[10:11], 16, v209
	v_ashrrev_i32_e32 v12, 2, v2
	v_add_u32_e32 v2, 0x200, v2
	v_cndmask_b32_e64 v6, v3, v11, s[10:11]
	v_add_u32_e32 v6, v6, v209
	v_ashrrev_i32_e32 v7, 31, v6
	v_ashrrev_i32_e32 v5, 31, v4
	v_lshlrev_b64 v[6:7], 12, v[6:7]
	v_ashrrev_i32_e32 v210, 5, v2
	v_lshl_add_u64 v[4:5], v[4:5], 1, s[16:17]
	v_lshl_add_u64 v[6:7], v[182:183], 0, v[6:7]
	v_add_u32_e32 v13, s38, v12
	s_mov_b32 s41, 0x10200
	v_cmp_gt_i32_e64 s[12:13], 16, v210
	s_waitcnt vmcnt(63) expcnt(7) lgkmcnt(15)
	s_barrier
	v_mad_i64_i32 v[8:9], s[4:5], v13, s41, v[4:5]
	global_load_dwordx4 v[162:165], v[6:7], off
	global_load_dwordx4 v[166:169], v[8:9], off
	v_ashrrev_i32_e32 v6, 2, v2
	v_cndmask_b32_e64 v2, v3, v11, s[12:13]
	v_add_u32_e32 v2, v2, v210
	v_ashrrev_i32_e32 v3, 31, v2
	v_lshlrev_b64 v[2:3], 12, v[2:3]
	v_lshl_add_u64 v[2:3], v[182:183], 0, v[2:3]
	v_add_u32_e32 v7, s38, v6
	global_load_dwordx4 v[170:173], v[2:3], off
	v_mad_i64_i32 v[2:3], s[4:5], v7, s41, v[4:5]
	global_load_dwordx4 v[174:177], v[2:3], off
	v_mad_i64_i32 v[184:185], s[4:5], v13, s41, 0
	v_mad_i64_i32 v[186:187], s[4:5], v7, s41, 0
	v_mov_b32_e32 v2, 0x3fb8aa3b
	s_movk_i32 s5, 0x210
	v_and_b32_e32 v212, 48, v10
	v_mul_lo_u32 v213, v209, s5
	s_movk_i32 s4, 0x50
	v_add_u32_e32 v3, 0, v212
	v_mul_lo_u32 v214, v12, s4
	v_mul_lo_u32 v215, v210, s5
	v_mul_lo_u32 v216, v6, s4
	v_mov_b32_e32 v22, 0
	s_mov_b32 s38, 3
	s_mov_b32 s39, 0
	v_lshlrev_b32_e32 v211, 3, v208
	v_mul_u32_u24_e32 v217, 0x210, v207
	v_mul_u32_u24_e32 v218, 0x50, v207
	v_mov_b32_e32 v23, v22
	v_mov_b32_e32 v24, v22
	v_mov_b32_e32 v25, v22
	v_mov_b32_e32 v50, v22
	v_mov_b32_e32 v51, v22
	v_mov_b32_e32 v52, v22
	v_mov_b32_e32 v53, v22
	v_mov_b32_e32 v58, v22
	v_mov_b32_e32 v59, v22
	s_waitcnt vmcnt(11)
	v_readfirstlane_b32 s40, v179
	v_mov_b32_e32 v60, v22
	v_mov_b32_e32 v61, v22
	v_mul_f32_e32 v179, s40, v2
	v_add_u32_e32 v2, 0, v180
	v_add_u32_e32 v4, v2, v213
	v_add_u32_e32 v2, v2, v215
	s_add_i32 s40, s37, 32
	v_mov_b32_e32 v70, v22
	v_mov_b32_e32 v71, v22
	v_mov_b32_e32 v72, v22
	v_mov_b32_e32 v73, v22
	v_mov_b32_e32 v82, v22
	v_mov_b32_e32 v83, v22
	v_mov_b32_e32 v84, v22
	v_mov_b32_e32 v85, v22
	v_mov_b32_e32 v90, v22
	v_mov_b32_e32 v91, v22
	v_mov_b32_e32 v92, v22
	v_mov_b32_e32 v93, v22
	v_mov_b32_e32 v102, v22
	v_mov_b32_e32 v103, v22
	v_mov_b32_e32 v104, v22
	v_mov_b32_e32 v105, v22
	v_mov_b32_e32 v130, v22
	v_mov_b32_e32 v131, v22
	v_mov_b32_e32 v132, v22
	v_mov_b32_e32 v133, v22
	v_mov_b32_e32 v42, v22
	v_mov_b32_e32 v43, v22
	v_mov_b32_e32 v44, v22
	v_mov_b32_e32 v45, v22
	v_mov_b32_e32 v34, v22
	v_mov_b32_e32 v35, v22
	v_mov_b32_e32 v36, v22
	v_mov_b32_e32 v37, v22
	v_mov_b32_e32 v26, v22
	v_mov_b32_e32 v27, v22
	v_mov_b32_e32 v28, v22
	s_waitcnt vmcnt(3)
	ds_write_b128 v4, v[162:165]
	v_add_u32_e32 v4, v3, v214
	s_waitcnt vmcnt(2)
	ds_write_b128 v4, v[166:169] offset:16896
	v_mov_b32_e32 v29, v22
	v_mov_b32_e32 v18, v22
	v_mov_b32_e32 v19, v22
	v_mov_b32_e32 v20, v22
	v_mov_b32_e32 v21, v22
	v_mov_b32_e32 v14, v22
	s_waitcnt vmcnt(1)
	ds_write_b128 v2, v[170:173]
	v_add_u32_e32 v2, v3, v216
	v_mov_b32_e32 v15, v22
	s_waitcnt vmcnt(0)
	ds_write_b128 v2, v[174:177] offset:16896
	v_mov_b32_e32 v16, v22
	v_mov_b32_e32 v17, v22
	v_mov_b32_e32 v10, v22
	v_mov_b32_e32 v11, v22
	v_mov_b32_e32 v12, v22
	v_mov_b32_e32 v13, v22
	v_mov_b32_e32 v6, v22
	v_mov_b32_e32 v7, v22
	v_mov_b32_e32 v8, v22
	v_mov_b32_e32 v9, v22
	v_mov_b32_e32 v2, v22
	v_mov_b32_e32 v3, v22
	v_mov_b32_e32 v4, v22
	v_mov_b32_e32 v5, v22
	v_mov_b32_e32 v158, v22
	v_mov_b32_e32 v159, v22
	v_mov_b32_e32 v160, v22
	v_mov_b32_e32 v161, v22
	v_mov_b32_e32 v154, v22
	v_mov_b32_e32 v155, v22
	v_mov_b32_e32 v156, v22
	v_mov_b32_e32 v157, v22
	v_mov_b32_e32 v150, v22
	v_mov_b32_e32 v151, v22
	v_mov_b32_e32 v152, v22
	v_mov_b32_e32 v153, v22
	v_mov_b32_e32 v110, v22
	v_mov_b32_e32 v111, v22
	v_mov_b32_e32 v112, v22
	v_mov_b32_e32 v113, v22
	v_mov_b32_e32 v106, v22
	v_mov_b32_e32 v107, v22
	v_mov_b32_e32 v108, v22
	v_mov_b32_e32 v109, v22
	v_mov_b32_e32 v98, v22
	v_mov_b32_e32 v99, v22
	v_mov_b32_e32 v100, v22
	v_mov_b32_e32 v101, v22
	v_mov_b32_e32 v94, v22
	v_mov_b32_e32 v95, v22
	v_mov_b32_e32 v96, v22
	v_mov_b32_e32 v97, v22
	v_mov_b32_e32 v86, v22
	v_mov_b32_e32 v87, v22
	v_mov_b32_e32 v88, v22
	v_mov_b32_e32 v89, v22
	v_mov_b32_e32 v78, v22
	v_mov_b32_e32 v79, v22
	v_mov_b32_e32 v80, v22
	v_mov_b32_e32 v81, v22
	v_mov_b32_e32 v74, v22
	v_mov_b32_e32 v75, v22
	v_mov_b32_e32 v76, v22
	v_mov_b32_e32 v77, v22
	v_mov_b32_e32 v66, v22
	v_mov_b32_e32 v67, v22
	v_mov_b32_e32 v68, v22
	v_mov_b32_e32 v69, v22
	v_mov_b32_e32 v62, v22
	v_mov_b32_e32 v63, v22
	v_mov_b32_e32 v64, v22
	v_mov_b32_e32 v65, v22
	v_mov_b32_e32 v54, v22
	v_mov_b32_e32 v55, v22
	v_mov_b32_e32 v56, v22
	v_mov_b32_e32 v57, v22
	v_mov_b32_e32 v46, v22
	v_mov_b32_e32 v47, v22
	v_mov_b32_e32 v48, v22
	v_mov_b32_e32 v49, v22
	v_mov_b32_e32 v38, v22
	v_mov_b32_e32 v39, v22
	v_mov_b32_e32 v40, v22
	v_mov_b32_e32 v41, v22
	v_mov_b32_e32 v30, v22
	v_mov_b32_e32 v31, v22
	v_mov_b32_e32 v32, v22
	v_mov_b32_e32 v33, v22
	v_mov_b32_e32 v188, v22
	v_mov_b32_e32 v189, v22
	v_readfirstlane_b32 s4, v206
	s_nop 3
	s_bitcmp1_b32 s4, 8
	s_cbranch_scc0 .Lprio_d_skip
	s_setprio 1
; __device__ __forceinline__ void wg_diff_task(ParamsCP pp, int layer, LAS unsigned char* lds, int b, int h, int qb, int tid_in) {
;     ...
;     { const bf16_t* qp = PROJ + (size_t)(qrow0 + c16) * PP + qcol + 8 * quad;
; #pragma unroll
;         for (int ks = 0; ks < 4; ++ks) { qf0[ks] = *(const bf16x8*)(qp + 32 * ks); qf1[ks] = *(const bf16x8*)(qp + 128 + 32 * ks); } }
; __device__ __forceinline__ void mixer_phase(ParamsCP pp, int layer, LAS unsigned char* lds, int tid) {
;     ...
;         if (tid == 0) *flag = atomicAdd(ctrw, 1u);
.Lprio_d_skip:
	s_mov_b32 exec_lo, 0xffff0000
	s_mov_b32 exec_hi, 0xffff0000
	v_swap_b32 v114, v116
	v_swap_b32 v115, v117
	v_swap_b32 v118, v120
	v_swap_b32 v119, v121
	v_swap_b32 v122, v124
	v_swap_b32 v123, v125
	v_swap_b32 v126, v128
	v_swap_b32 v127, v129
	v_swap_b32 v134, v136
	v_swap_b32 v135, v137
	v_swap_b32 v138, v140
	v_swap_b32 v139, v141
	v_swap_b32 v142, v144
	v_swap_b32 v143, v145
	v_swap_b32 v146, v148
	v_swap_b32 v147, v149
	s_mov_b64 exec, -1
	s_and_saveexec_b64 s[4:5], s[6:7]
	s_cbranch_execz .Lmx_d_nowr
	v_mov_b32_e32 v253, s70
	ds_write_b32 v253, v252

; #define LAS __attribute__((address_space(3)))
; __device__ __forceinline__ float fast_exp2(float x) { return __builtin_amdgcn_exp2f(x); }
; __device__ __forceinline__ void wg_diff_task(ParamsCP pp, int layer, LAS unsigned char* lds, int b, int h, int qb, int tid_in) {
;     ...
;     for (int st = 0; st < 65; ++st) {
;         const int buf = st & 1;
;         if (st + 1 < 65) DF_ISSUE(st + 1);
;         const LAS unsigned char* kb = lds + buf * DF_BUF; const LAS unsigned char* vb = kb + DF_KBYTES;
;         const bool v1 = 2 * st + 1 < 129;
;         bf16x8 pf0, pf1;
;         {   bf16x8 k0[4], k1[4];
; #pragma unroll
;             for (int ks = 0; ks < 4; ++ks) { k0[ks] = *(const LAS bf16x8*)(kb + c16 * DF_KP + (32 * ks + 8 * quad) * 2); k1[ks] = *(const LAS bf16x8*)(kb + (16 + c16) * DF_KP + (32 * ks + 8 * quad) * 2); }
;             const f32x4 s0 = st_mma<4>(k0, qf0), s1 = st_mma<4>(k1, qf0);
;             float p0[4], p1[4];
; #pragma unroll
;             for (int r = 0; r < 4; ++r) { p0[r] = fast_exp2(s0[r] * sc - cb); p1[r] = v1 ? fast_exp2(s1[r] * sc - cb) : 0.f; ls0 += p0[r] + p1[r]; }
;             pf0 = pack_p(p0, p1); }
;         {   bf16x8 k0[4], k1[4];
; #pragma unroll
;             for (int ks = 0; ks < 4; ++ks) { k0[ks] = *(const LAS bf16x8*)(kb + c16 * DF_KP + 256 + (32 * ks + 8 * quad) * 2); k1[ks] = *(const LAS bf16x8*)(kb + (16 + c16) * DF_KP + 256 + (32 * ks + 8 * quad) * 2); }
;             const f32x4 s0 = st_mma<4>(k0, qf1), s1 = st_mma<4>(k1, qf1);
;             float p0[4], p1[4];
; #pragma unroll
;             for (int r = 0; r < 4; ++r) { p0[r] = fast_exp2(s0[r] * sc - cb); p1[r] = v1 ? fast_exp2(s1[r] * sc - cb) : 0.f; ls1 += p0[r] + p1[r]; }
;             pf1 = pack_p(p0, p1); }
.LBB0_442:
	s_and_b32 s41, s39, 1
	s_mul_i32 s50, s41, 0x9200
	v_add3_u32 v219, s50, v217, v0
	v_xor_b32_e32 v220, 8, v219
	ds_read_b64 v[190:191], v219
	ds_read_b64 v[192:193], v220
	ds_read_b64 v[194:195], v219 offset:64
	ds_read_b64 v[196:197], v220 offset:64
	ds_read_b64 v[198:199], v219 offset:8448
	ds_read_b64 v[200:201], v220 offset:8448
	ds_read_b64 v[202:203], v219 offset:8512
	ds_read_b64 v[204:205], v220 offset:8512
	s_cmp_eq_u32 s39, 64
	s_cselect_b64 s[48:49], -1, 0
	s_cmp_lg_u32 s39, 64
	s_cselect_b64 s[4:5], -1, 0
	s_and_b64 vcc, exec, s[48:49]
	s_cbranch_vccnz .LBB0_444
	s_min_u32 s41, s38, 0x80
	s_lshl_b32 s41, s41, 4
	s_add_i32 s41, s41, s37
	s_waitcnt vmcnt(3)
	v_mov_b32_e32 v162, s41
	s_waitcnt vmcnt(1)
	v_mov_b32_e32 v172, s40
	v_cndmask_b32_e64 v162, v162, v172, s[8:9]
	s_add_i32 s50, s41, -16
	v_or_b32_e32 v162, v162, v181
	v_ashrrev_i32_e32 v163, 31, v162
	v_mov_b32_e32 v173, s50
	v_lshl_add_u64 v[170:171], v[162:163], 1, s[16:17]
	v_cndmask_b32_e64 v162, v173, v172, s[10:11]
	v_cndmask_b32_e64 v172, v173, v172, s[12:13]
	v_add_u32_e32 v162, v162, v209
	v_add_u32_e32 v172, v172, v210
	v_ashrrev_i32_e32 v163, 31, v162
	v_ashrrev_i32_e32 v173, 31, v172
	v_lshlrev_b64 v[162:163], 12, v[162:163]
	v_lshlrev_b64 v[172:173], 12, v[172:173]
	v_lshl_add_u64 v[162:163], v[182:183], 0, v[162:163]
	v_lshl_add_u64 v[166:167], v[170:171], 0, v[184:185]
	v_lshl_add_u64 v[172:173], v[182:183], 0, v[172:173]
	s_waitcnt vmcnt(0)
	v_lshl_add_u64 v[174:175], v[170:171], 0, v[186:187]
	global_load_dwordx4 v[162:165], v[162:163], off
	s_nop 0
	global_load_dwordx4 v[166:169], v[166:167], off
	s_nop 0
	global_load_dwordx4 v[170:173], v[172:173], off
	s_nop 0
	global_load_dwordx4 v[174:177], v[174:175], off
.LBB0_444:
	s_and_b32 s41, s39, 1
	s_mul_i32 s50, s41, 0x9200
	s_add_i32 s50, s50, 0
	s_andn2_b64 vcc, exec, s[4:5]
	s_waitcnt lgkmcnt(6)
	v_mfma_f32_16x16x32_bf16 v[190:193], v[190:193], v[114:117], 0
	s_waitcnt lgkmcnt(4)
	v_mfma_f32_16x16x32_bf16 v[190:193], v[194:197], v[118:121], v[190:193]
	ds_read_b64 v[194:195], v219 offset:128
	ds_read_b64 v[196:197], v220 offset:128
	s_waitcnt lgkmcnt(4)
	v_mfma_f32_16x16x32_bf16 v[198:201], v[198:201], v[114:117], 0
	s_waitcnt lgkmcnt(2)
	v_mfma_f32_16x16x32_bf16 v[198:201], v[202:205], v[118:121], v[198:201]
	ds_read_b64 v[202:203], v219 offset:192
	ds_read_b64 v[204:205], v220 offset:192
	s_waitcnt lgkmcnt(2)
	v_mfma_f32_16x16x32_bf16 v[190:193], v[194:197], v[134:137], v[190:193]
	ds_read_b64 v[194:195], v219 offset:8576
	ds_read_b64 v[196:197], v220 offset:8576
	s_waitcnt lgkmcnt(2)
	v_mfma_f32_16x16x32_bf16 v[202:205], v[202:205], v[138:141], v[190:193]
	s_nop 4
	ds_read_b64 v[190:191], v219 offset:8640
	ds_read_b64 v[192:193], v220 offset:8640
	s_waitcnt lgkmcnt(2)
	v_mfma_f32_16x16x32_bf16 v[194:197], v[194:197], v[134:137], v[198:201]
	s_nop 2
	ds_read_b64 v[198:199], v219 offset:256
	ds_read_b64 v[200:201], v220 offset:256
	ds_read_b64 v[242:243], v219 offset:320
	ds_read_b64 v[244:245], v220 offset:320
	ds_read_b64 v[246:247], v219 offset:384
	ds_read_b64 v[248:249], v220 offset:384
	ds_read_b64 v[250:251], v219 offset:448
	ds_read_b64 v[252:253], v220 offset:448
	s_waitcnt lgkmcnt(6)
	v_mfma_f32_16x16x32_bf16 v[198:201], v[198:201], v[122:125], 0
	ds_read_b64 v[232:233], v219 offset:8896
	ds_read_b64 v[234:235], v220 offset:8896
	s_waitcnt lgkmcnt(6)
	v_mfma_f32_16x16x32_bf16 v[198:201], v[242:245], v[126:129], v[198:201]
	ds_read_b64 v[242:243], v219 offset:8704
	ds_read_b64 v[244:245], v220 offset:8704
	s_waitcnt lgkmcnt(6)
	v_mfma_f32_16x16x32_bf16 v[198:201], v[246:249], v[142:145], v[198:201]
	ds_read_b64 v[246:247], v219 offset:8768
	ds_read_b64 v[248:249], v220 offset:8768
	v_mfma_f32_16x16x32_bf16 v[194:197], v[190:193], v[138:141], v[194:197]
	v_fma_f32 v190, v202, s89, -v179
	v_exp_f32_e32 v190, v190
	s_waitcnt lgkmcnt(6)
	v_mfma_f32_16x16x32_bf16 v[198:201], v[250:253], v[146:149], v[198:201]
	ds_read_b64 v[250:251], v219 offset:8832
	ds_read_b64 v[252:253], v220 offset:8832
	s_nop 2
	v_fma_f32 v191, v194, s89, -v179
	v_exp_f32_e32 v220, v191
	s_waitcnt lgkmcnt(4)
	v_mfma_f32_16x16x32_bf16 v[242:245], v[242:245], v[122:125], 0
	v_fma_f32 v191, v203, s89, -v179
	v_exp_f32_e32 v192, v191
	v_fma_f32 v191, v195, s89, -v179
	s_waitcnt lgkmcnt(2)
	v_mfma_f32_16x16x32_bf16 v[242:245], v[246:249], v[126:129], v[242:245]
	v_exp_f32_e32 v221, v191
	v_fma_f32 v191, v204, s89, -v179
	v_exp_f32_e32 v194, v191
	v_fma_f32 v191, v196, s89, -v179
	v_exp_f32_e32 v224, v191
	v_fma_f32 v191, v205, s89, -v179
	s_waitcnt lgkmcnt(0)
; #define LAS __attribute__((address_space(3)))
; __device__ __forceinline__ float fast_exp2(float x) { return __builtin_amdgcn_exp2f(x); }
; __device__ __forceinline__ f32x4 mfma16(bf16x8 a, bf16x8 b, f32x4 c) { return __builtin_amdgcn_mfma_f32_16x16x32_bf16(a, b, c, 0, 0, 0); }
; #define DF_COMMIT(buf) do { LAS unsigned char* bb_ = lds + (buf) * DF_BUF; \
;         _Pragma("unroll") for (int i_ = 0; i_ < 2; ++i_) { const int id_ = tid + 512 * i_, kr_ = id_ >> 5, kc_ = id_ & 31, vr_ = id_ >> 2, vc_ = id_ & 3; \
;             *(LAS u32x4*)(bb_ + kr_ * DF_KP + kc_ * 16) = kreg[i_]; *(LAS u32x4*)(bb_ + DF_KBYTES + vr_ * VP + vc_ * 16) = vreg[i_]; } } while (0)
; __device__ __forceinline__ void wg_diff_task(ParamsCP pp, int layer, LAS unsigned char* lds, int b, int h, int qb, int tid_in) {
;     ...
;             for (int r = 0; r < 4; ++r) { p0[r] = fast_exp2(s0[r] * sc - cb); p1[r] = v1 ? fast_exp2(s1[r] * sc - cb) : 0.f; ls0 += p0[r] + p1[r]; }
;             pf0 = pack_p(p0, p1); }
;         {   bf16x8 k0[4], k1[4];
; #pragma unroll
;             for (int ks = 0; ks < 4; ++ks) { k0[ks] = *(const LAS bf16x8*)(kb + c16 * DF_KP + 256 + (32 * ks + 8 * quad) * 2); k1[ks] = *(const LAS bf16x8*)(kb + (16 + c16) * DF_KP + 256 + (32 * ks + 8 * quad) * 2); }
;             const f32x4 s0 = st_mma<4>(k0, qf1), s1 = st_mma<4>(k1, qf1);
;             float p0[4], p1[4];
; #pragma unroll
;             for (int r = 0; r < 4; ++r) { p0[r] = fast_exp2(s0[r] * sc - cb); p1[r] = v1 ? fast_exp2(s1[r] * sc - cb) : 0.f; ls1 += p0[r] + p1[r]; }
;             pf1 = pack_p(p0, p1); }
; #pragma unroll
;         for (int e0 = 0; e0 < 16; ++e0) {
;             const u32x2 va = *(const LAS u32x2*)(vb + (e0 * 16 + c16) * VP + 8 * quad), vbb = *(const LAS u32x2*)(vb + (e0 * 16 + c16) * VP + 32 + 8 * quad);
;             u32x4 w; w.x = va.x; w.y = va.y; w.z = vbb.x; w.w = vbb.y; const bf16x8 vf = __builtin_bit_cast(bf16x8, w);
;             acc0[e0] = mfma16(pf0, vf, acc0[e0]); acc1[e0] = mfma16(pf1, vf, acc1[e0]);
;         }
;         if (st + 1 < 65) DF_COMMIT(buf ^ 1);
	v_mfma_f32_16x16x32_bf16 v[202:205], v[250:253], v[142:145], v[242:245]
	v_exp_f32_e32 v196, v191
	v_fma_f32 v191, v197, s89, -v179
	v_exp_f32_e32 v219, v191
	v_mfma_f32_16x16x32_bf16 v[202:205], v[232:235], v[146:149], v[202:205]
	v_fma_f32 v191, v198, s89, -v179
	v_exp_f32_e32 v191, v191
	v_add3_u32 v250, s50, v218, v211
	v_add_u32_e32 v251, 0x4000, v250
	v_cvt_pk_bf16_f32 v242, v190, v192
	s_nop 2
	v_fma_f32 v193, v202, s89, -v179
	v_exp_f32_e32 v198, v193
	v_fma_f32 v193, v199, s89, -v179
	v_fma_f32 v195, v203, s89, -v179
	v_fma_f32 v197, v204, s89, -v179
	v_fma_f32 v199, v205, s89, -v179
	v_exp_f32_e32 v203, v195
	v_fma_f32 v195, v200, s89, -v179
	v_exp_f32_e32 v234, v197
	v_fma_f32 v197, v201, s89, -v179
	v_exp_f32_e32 v205, v199
	v_exp_f32_e32 v193, v193
	v_exp_f32_e32 v195, v195
	v_exp_f32_e32 v197, v197
	v_cndmask_b32_e64 v199, v198, 0, s[48:49]
	v_cndmask_b32_e64 v198, v220, 0, s[48:49]
	v_cndmask_b32_e64 v200, v221, 0, s[48:49]
	v_cndmask_b32_e64 v202, v224, 0, s[48:49]
	v_cndmask_b32_e64 v204, v219, 0, s[48:49]
	v_cndmask_b32_e64 v201, v203, 0, s[48:49]
	v_cndmask_b32_e64 v203, v234, 0, s[48:49]
	v_cndmask_b32_e64 v205, v205, 0, s[48:49]
	v_cvt_pk_bf16_f32 v243, v194, v196
	v_cvt_pk_bf16_f32 v232, v191, v193
	v_cvt_pk_bf16_f32 v233, v195, v197
	ds_read_b64 v[246:247], v250 offset:16896
	ds_read_b64 v[248:249], v250 offset:16928
	v_cvt_pk_bf16_f32 v244, v198, v200
	v_cvt_pk_bf16_f32 v245, v202, v204
	v_cvt_pk_bf16_f32 v234, v199, v201
	v_cvt_pk_bf16_f32 v235, v203, v205
	v_pk_add_f32 v[190:191], v[190:191], v[198:199]
	v_pk_add_f32 v[192:193], v[192:193], v[200:201]
	v_pk_add_f32 v[188:189], v[188:189], v[190:191]
	v_pk_add_f32 v[194:195], v[194:195], v[202:203]
	v_pk_add_f32 v[188:189], v[192:193], v[188:189]
	v_pk_add_f32 v[196:197], v[196:197], v[204:205]
	v_pk_add_f32 v[188:189], v[194:195], v[188:189]
	v_pk_add_f32 v[188:189], v[196:197], v[188:189]
	ds_read_b64 v[190:191], v250 offset:18176
	ds_read_b64 v[192:193], v250 offset:18208
	ds_read_b64 v[194:195], v250 offset:19456
	ds_read_b64 v[196:197], v250 offset:19488
	ds_read_b64 v[198:199], v250 offset:20736
	ds_read_b64 v[200:201], v250 offset:20768
	ds_read_b64 v[202:203], v250 offset:22016
	ds_read_b64 v[204:205], v250 offset:22048
	s_waitcnt lgkmcnt(8)
	v_mfma_f32_16x16x32_bf16 v[158:161], v[242:245], v[246:249], v[158:161]
	v_mfma_f32_16x16x32_bf16 v[130:133], v[232:235], v[246:249], v[130:133]
	ds_read_b64 v[246:247], v250 offset:23296
	ds_read_b64 v[248:249], v250 offset:23328
	s_waitcnt lgkmcnt(8)
	v_mfma_f32_16x16x32_bf16 v[154:157], v[242:245], v[190:193], v[154:157]
	v_mfma_f32_16x16x32_bf16 v[102:105], v[232:235], v[190:193], v[102:105]
	ds_read_b64 v[190:191], v250 offset:24576
	ds_read_b64 v[192:193], v250 offset:24608
	s_waitcnt lgkmcnt(8)
	v_mfma_f32_16x16x32_bf16 v[150:153], v[242:245], v[194:197], v[150:153]
	v_mfma_f32_16x16x32_bf16 v[90:93], v[232:235], v[194:197], v[90:93]
	ds_read_b64 v[194:195], v250 offset:25856
	ds_read_b64 v[196:197], v250 offset:25888
	s_waitcnt lgkmcnt(8)
	v_mfma_f32_16x16x32_bf16 v[110:113], v[242:245], v[198:201], v[110:113]
	v_mfma_f32_16x16x32_bf16 v[82:85], v[232:235], v[198:201], v[82:85]
	ds_read_b64 v[198:199], v250 offset:27136
	ds_read_b64 v[200:201], v250 offset:27168
	s_waitcnt lgkmcnt(8)
	v_mfma_f32_16x16x32_bf16 v[106:109], v[242:245], v[202:205], v[106:109]
	v_mfma_f32_16x16x32_bf16 v[70:73], v[232:235], v[202:205], v[70:73]
	ds_read_b64 v[202:203], v250 offset:28416
	ds_read_b64 v[204:205], v250 offset:28448
	s_waitcnt lgkmcnt(8)
	v_mfma_f32_16x16x32_bf16 v[98:101], v[242:245], v[246:249], v[98:101]
	v_mfma_f32_16x16x32_bf16 v[58:61], v[232:235], v[246:249], v[58:61]
	ds_read_b64 v[246:247], v250 offset:29696
	ds_read_b64 v[248:249], v250 offset:29728
	s_waitcnt lgkmcnt(8)
	v_mfma_f32_16x16x32_bf16 v[94:97], v[242:245], v[190:193], v[94:97]
	v_mfma_f32_16x16x32_bf16 v[50:53], v[232:235], v[190:193], v[50:53]
	ds_read_b64 v[190:191], v250 offset:30976
	ds_read_b64 v[192:193], v250 offset:31008
	s_waitcnt lgkmcnt(8)
	v_mfma_f32_16x16x32_bf16 v[86:89], v[242:245], v[194:197], v[86:89]
	v_mfma_f32_16x16x32_bf16 v[22:25], v[232:235], v[194:197], v[22:25]
	ds_read_b64 v[194:195], v250 offset:32256
	ds_read_b64 v[196:197], v250 offset:32288
	s_waitcnt lgkmcnt(8)
	v_mfma_f32_16x16x32_bf16 v[78:81], v[242:245], v[198:201], v[78:81]
	v_mfma_f32_16x16x32_bf16 v[42:45], v[232:235], v[198:201], v[42:45]
	ds_read_b64 v[198:199], v250 offset:33536
	ds_read_b64 v[200:201], v250 offset:33568
	s_waitcnt lgkmcnt(8)
	v_mfma_f32_16x16x32_bf16 v[74:77], v[242:245], v[202:205], v[74:77]
	v_mfma_f32_16x16x32_bf16 v[34:37], v[232:235], v[202:205], v[34:37]
	ds_read_b64 v[202:203], v250 offset:34816
	ds_read_b64 v[204:205], v250 offset:34848
	s_waitcnt lgkmcnt(8)
	v_mfma_f32_16x16x32_bf16 v[66:69], v[242:245], v[246:249], v[66:69]
	v_mfma_f32_16x16x32_bf16 v[26:29], v[232:235], v[246:249], v[26:29]
	ds_read_b64 v[246:247], v250 offset:36096
	ds_read_b64 v[248:249], v250 offset:36128
	s_cbranch_vccnz .Ldf_tail_nw
	s_xor_b32 s4, s41, 1
	s_mul_i32 s4, s4, 0x9200
	s_add_i32 s4, s4, 0
	v_add_u32_e32 v219, s4, v180
	v_add_u32_e32 v220, v219, v213
	v_add_u32_e32 v221, s4, v212
	v_add_u32_e32 v224, v221, v214
	v_add_u32_e32 v219, v219, v215
	v_add_u32_e32 v221, v221, v216
	s_waitcnt lgkmcnt(8)
	v_mfma_f32_16x16x32_bf16 v[62:65], v[242:245], v[190:193], v[62:65]
	v_mfma_f32_16x16x32_bf16 v[18:21], v[232:235], v[190:193], v[18:21]
	s_waitcnt vmcnt(3)
	ds_write_b128 v220, v[162:165]
	s_waitcnt lgkmcnt(7)
	v_mfma_f32_16x16x32_bf16 v[54:57], v[242:245], v[194:197], v[54:57]
	v_mfma_f32_16x16x32_bf16 v[14:17], v[232:235], v[194:197], v[14:17]
	s_waitcnt vmcnt(2)
	ds_write_b128 v224, v[166:169] offset:16896
	s_waitcnt lgkmcnt(6)
	v_mfma_f32_16x16x32_bf16 v[46:49], v[242:245], v[198:201], v[46:49]
	v_mfma_f32_16x16x32_bf16 v[10:13], v[232:235], v[198:201], v[10:13]
	s_waitcnt vmcnt(1)
	ds_write_b128 v219, v[170:173]
	s_waitcnt lgkmcnt(5)
	v_mfma_f32_16x16x32_bf16 v[38:41], v[242:245], v[202:205], v[38:41]
	v_mfma_f32_16x16x32_bf16 v[6:9], v[232:235], v[202:205], v[6:9]
	s_waitcnt vmcnt(0)
	ds_write_b128 v221, v[174:177] offset:16896
	s_waitcnt lgkmcnt(4)
	v_mfma_f32_16x16x32_bf16 v[30:33], v[242:245], v[246:249], v[30:33]
	v_mfma_f32_16x16x32_bf16 v[2:5], v[232:235], v[246:249], v[2:5]
	s_branch .LBB0_441
